# attention item: epilogue gate loads issued behind the first-tile LDS-DMA and left in flight (first-tile wait vmcnt(8))
# baseline (speedup 1.0000x reference)
.LBB0_623:
	s_and_b64 vcc, exec, s[74:75]
	s_cbranch_vccz .LBB0_591
	s_and_b32 s48, s84, 63
	s_lshr_b32 s78, s84, 6
	s_sub_i32 s79, 15, s78
	s_mul_i32 s76, s48, 0xc0000
	s_add_u32 s74, s87, s76
	s_addc_u32 s75, s88, 0
	s_add_u32 s76, s89, s76
	s_addc_u32 s77, s91, 0
	s_lshl_b32 s85, s48, 19
	v_lshl_add_u32 v4, s79, 8, v157
	s_lshl_b32 s48, s84, 9
	s_and_b32 s48, s48, 0x7000
	v_ashrrev_i32_e32 v5, 31, v4
	v_or_b32_e32 v2, v4, v156
	v_lshl_add_u64 v[4:5], v[4:5], 0, s[48:49]
	v_or_b32_e32 v221, v5, v1
	v_or_b32_e32 v220, v4, v156
	s_lshl_b32 s48, s84, 6
	v_mov_b64_e32 v[6:7], s[74:75]
	v_lshlrev_b64 v[4:5], 10, v[220:221]
	s_and_b32 s48, s48, 0x1c0
	v_mad_i64_i32 v[6:7], s[74:75], v2, s86, v[6:7]
	v_lshl_add_u64 v[4:5], s[66:67], 0, v[4:5]
	s_lshl_b32 s48, s48, 1
	v_lshlrev_b32_e32 v222, 1, v158
	v_mov_b32_e32 v223, v3
	v_lshl_add_u64 v[4:5], v[4:5], 0, s[48:49]
	v_mov_b32_e32 v183, v3
	s_add_u32 s74, s92, s85
	v_lshl_add_u64 v[6:7], v[6:7], 0, v[222:223]
	v_lshl_add_u64 v[4:5], v[4:5], 0, v[182:183]
	s_addc_u32 s75, s93, 0
	v_mov_b32_e32 v191, v3
	global_load_dwordx4 v[132:135], v[6:7], off
	global_load_dwordx4 v[136:139], v[6:7], off offset:32
	global_load_dwordx4 v[140:143], v[6:7], off offset:64
	global_load_dwordx4 v[144:147], v[6:7], off offset:96
	global_load_dwordx4 v[148:151], v[6:7], off offset:128
	global_load_dwordx4 v[152:155], v[6:7], off offset:160
	v_mov_b32_e32 v130, v4
	v_mov_b32_e32 v131, v5
	v_lshl_add_u64 v[8:9], s[76:77], 0, v[190:191]
	v_mov_b32_e32 v193, v3
	v_lshl_add_u64 v[10:11], s[74:75], 0, v[164:165]
	v_mov_b32_e32 v195, v3
	v_mov_b32_e32 v185, v3
	v_lshl_add_u64 v[8:9], v[8:9], 0, v[192:193]
	v_lshl_add_u64 v[10:11], v[10:11], 0, v[194:195]
	v_add_u32_e32 v2, 0, v245
	v_lshl_add_u64 v[4:5], s[76:77], 0, v[184:185]
	v_mov_b32_e32 v187, v3
	v_lshl_add_u64 v[6:7], s[76:77], 0, v[162:163]
	v_cndmask_b32_e64 v9, v11, v9, s[40:41]
	v_cndmask_b32_e64 v8, v10, v8, s[40:41]
	v_lshl_add_u64 v[10:11], s[76:77], 0, v[168:169]
	v_readfirstlane_b32 s76, v2
	v_add_u32_e32 v2, 0, v246
	v_lshl_add_u64 v[4:5], v[4:5], 0, v[186:187]
	v_mov_b32_e32 v189, v3
	s_mov_b32 m0, s76
	v_readfirstlane_b32 s76, v2
	v_add_u32_e32 v2, 0, v251
	v_lshl_add_u64 v[6:7], v[6:7], 0, v[188:189]
	v_mov_b32_e32 v197, v3
	v_lshl_add_u64 v[12:13], s[74:75], 0, v[166:167]
	v_mov_b32_e32 v199, v3
	s_barrier
	global_load_lds_dwordx4 v[4:5], off
	s_mov_b32 m0, s76
	v_readfirstlane_b32 s76, v2
	v_add_u32_e32 v2, 0, v252
	v_lshl_add_u64 v[10:11], v[10:11], 0, v[196:197]
	v_lshl_add_u64 v[12:13], v[12:13], 0, v[198:199]
	global_load_lds_dwordx4 v[6:7], off
	s_mov_b32 m0, s76
	v_readfirstlane_b32 s76, v2
	v_cndmask_b32_e64 v11, v13, v11, s[42:43]
	v_cndmask_b32_e64 v10, v12, v10, s[42:43]
	global_load_lds_dwordx4 v[8:9], off
	s_mov_b32 m0, s76
	v_lshl_add_u64 v[12:13], s[74:75], 0, v[170:171]
	global_load_lds_dwordx4 v[10:11], off
	v_mov_b32_e32 v201, v3
	v_lshl_add_u64 v[224:225], v[12:13], 0, v[200:201]
	s_and_saveexec_b64 s[76:77], s[36:37]
	s_cbranch_execz .LBB0_626
	v_add_u32_e32 v2, 0, v247
	v_add_u32_e32 v2, 0x6800, v2
	s_nop 0
	v_readfirstlane_b32 s85, v2
	s_mov_b32 m0, s85
	s_nop 0
	global_load_lds_dwordx4 v[224:225], off
	v_lshl_add_u64 v[224:225], v[224:225], 0, s[70:71]

.LBB0_628:
	s_or_b64 exec, exec, s[74:75]
	global_load_dwordx2 v[218:219], v[130:131], off
	global_load_dwordx2 v[216:217], v[130:131], off offset:16
	global_load_dwordx2 v[214:215], v[130:131], off offset:32
	global_load_dwordx2 v[212:213], v[130:131], off offset:48
	global_load_dwordx2 v[210:211], v[130:131], off offset:64
	global_load_dwordx2 v[208:209], v[130:131], off offset:80
	global_load_dwordx2 v[206:207], v[130:131], off offset:96
	global_load_dwordx2 v[204:205], v[130:131], off offset:112
	s_cmpk_lt_u32 s84, 0x400
	s_waitcnt vmcnt(8) lgkmcnt(0)
	s_barrier
	s_cbranch_scc0 .LBB0_659
	v_lshlrev_b32_e32 v2, 1, v174
	v_lshlrev_b32_e32 v234, 1, v176
	v_mov_b32_e32 v235, v3
	s_lshl_b32 s74, s78, 1
	v_lshl_add_u32 v183, s79, 2, v244
	s_lshl_b32 s96, s79, 1
	v_lshl_add_u64 v[228:229], v[4:5], 0, s[72:73]
	v_lshl_add_u64 v[230:231], v[6:7], 0, s[72:73]
	v_lshl_add_u64 v[232:233], v[8:9], 0, v[2:3]
	v_lshl_add_u64 v[236:237], v[10:11], 0, v[234:235]
	s_sub_i32 s97, 32, s74
	v_mov_b32_e32 v238, v3
	v_mov_b32_e32 v239, v3
	v_mov_b32_e32 v4, v3
	v_mov_b32_e32 v5, v3
	v_mov_b32_e32 v6, v3
	v_mov_b32_e32 v7, v3
	v_mov_b32_e32 v8, v3
	v_mov_b32_e32 v9, v3
	v_mov_b32_e32 v10, v3
	v_mov_b32_e32 v11, v3
	v_mov_b32_e32 v12, v3
	v_mov_b32_e32 v13, v3
	v_mov_b32_e32 v14, v3
	v_mov_b32_e32 v15, v3
	v_mov_b32_e32 v16, v3
	v_mov_b32_e32 v17, v3
	v_mov_b32_e32 v18, v3
	v_mov_b32_e32 v19, v3
	v_mov_b32_e32 v20, v3
	v_mov_b32_e32 v21, v3
	v_mov_b32_e32 v22, v3
	v_mov_b32_e32 v23, v3
	v_mov_b32_e32 v24, v3
	v_mov_b32_e32 v25, v3
	v_mov_b32_e32 v26, v3
	v_mov_b32_e32 v27, v3
	v_mov_b32_e32 v28, v3
	v_mov_b32_e32 v29, v3
	v_mov_b32_e32 v30, v3
	v_mov_b32_e32 v31, v3
	v_mov_b32_e32 v32, v3
	v_mov_b32_e32 v33, v3
	v_mov_b32_e32 v34, v3
	v_mov_b32_e32 v35, v3
	s_mov_b32 s90, 0
	s_mov_b32 s86, 0
	s_branch .LBB0_632

.LBB0_659:
	s_waitcnt vmcnt(0)
	v_mov_b32_e32 v4, v3
	v_mov_b32_e32 v5, v3
	v_mov_b32_e32 v6, v3
	v_mov_b32_e32 v7, v3
	v_mov_b32_e32 v8, v3
	v_mov_b32_e32 v9, v3
	v_mov_b32_e32 v10, v3
	v_mov_b32_e32 v11, v3
	v_mov_b32_e32 v12, v3
	v_mov_b32_e32 v13, v3
	v_mov_b32_e32 v14, v3
	v_mov_b32_e32 v15, v3
	v_mov_b32_e32 v16, v3
	v_mov_b32_e32 v17, v3
	v_mov_b32_e32 v18, v3
	v_mov_b32_e32 v19, v3
	v_mov_b32_e32 v20, v3
	v_mov_b32_e32 v21, v3
	v_mov_b32_e32 v22, v3
	v_mov_b32_e32 v23, v3
	v_mov_b32_e32 v24, v3
	v_mov_b32_e32 v25, v3
	v_mov_b32_e32 v26, v3
	v_mov_b32_e32 v27, v3
	v_mov_b32_e32 v28, v3
	v_mov_b32_e32 v29, v3
	v_mov_b32_e32 v30, v3
	v_mov_b32_e32 v31, v3
	v_mov_b32_e32 v32, v3
	v_mov_b32_e32 v33, v3
	v_mov_b32_e32 v2, v3
	v_mov_b64_e32 v[34:35], v[32:33]
	v_mov_b32_e32 v238, 0
	v_mov_b64_e32 v[32:33], v[30:31]
	v_mov_b64_e32 v[30:31], v[28:29]
	v_mov_b64_e32 v[28:29], v[26:27]
	v_mov_b64_e32 v[26:27], v[24:25]
	v_mov_b64_e32 v[24:25], v[22:23]
	v_mov_b64_e32 v[22:23], v[20:21]
	v_mov_b64_e32 v[20:21], v[18:19]
	v_mov_b64_e32 v[18:19], v[16:17]
	v_mov_b64_e32 v[16:17], v[14:15]
	v_mov_b64_e32 v[14:15], v[12:13]
	v_mov_b64_e32 v[12:13], v[10:11]
	v_mov_b64_e32 v[10:11], v[8:9]
	v_mov_b64_e32 v[8:9], v[6:7]
	v_mov_b64_e32 v[6:7], v[4:5]
	v_mov_b64_e32 v[4:5], v[2:3]
	s_branch .LBB0_590
